# conv fix-up phase: four conditional halo-neighbour loads issued together un-waited, completed under the parameter loads' wait
# speedup vs baseline: 1.0164x; 1.0019x over previous
; __device__ __forceinline__ unsigned cvt_pk_bf16(float lo, float hi) { unsigned r; asm("v_cvt_pk_bf16_f32 %0, %1, %2" : "=v"(r) : "v"(lo), "v"(hi)); return r; }
; __global__ void __launch_bounds__(512, 2) mk_fwd(Args args) {
;     ...
;                     const int c = 256 * chunk + 4 * lane;
;                     const int na = ((c >> 7) << 8) + (c & 127), ng = na + 128;
;                     const f32x4 z4 = (f32x4){0.f, 0.f, 0.f, 0.f};
;                     const f32x4 ac = *(const f32x4*)(hc + na), gc = *(const f32x4*)(hc + ng);
;                     const f32x4 ap = hp ? *(const f32x4*)(hp + na) : z4, gp = hp ? *(const f32x4*)(hp + ng) : z4;
;                     const f32x4 an = hn ? *(const f32x4*)(hn + na) : z4, gn = hn ? *(const f32x4*)(hn + ng) : z4;
;                     const f32x4 av = *(const f32x4*)(cw + c) * ap + *(const f32x4*)(cw + FF2 + c) * ac + *(const f32x4*)(cw + 2 * FF2 + c) * an + *(const f32x4*)(cb + c);
;                     const f32x4 gv = *(const f32x4*)(cw + FFH + c) * gp + *(const f32x4*)(cw + FF2 + FFH + c) * gc + *(const f32x4*)(cw + 2 * FF2 + FFH + c) * gn + *(const f32x4*)(cb + FFH + c);
;                     f32x4 o;
; #pragma unroll
;                     for (int e = 0; e < 4; ++e) o[e] = av[e] * gv[e] / (1.0f + __expf(-gv[e]));
;                     u32x2 w; w.x = cvt_pk_bf16(o[0], o[1]); w.y = cvt_pk_bf16(o[2], o[3]);
;                     *(u32x2*)(GB + (size_t)row * FFH + c) = w;
.LBB0_695:
	s_mulk_i32 s14, 0xf500
	v_add_u32_e32 v50, s14, v60
	v_ashrrev_i32_e32 v51, 31, v50
	v_lshlrev_b64 v[6:7], 2, v[50:51]
	v_lshl_add_u64 v[2:3], s[0:1], 0, v[6:7]
	global_load_dwordx4 v[34:37], v[2:3], off
	v_lshl_add_u64 v[2:3], s[6:7], 0, v[6:7]
	global_load_dwordx4 v[38:41], v[2:3], off
	v_lshl_add_u64 v[2:3], s[8:9], 0, v[6:7]
	global_load_dwordx4 v[42:45], v[2:3], off
	v_lshl_add_u64 v[8:9], s[38:39], 0, v[6:7]
	global_load_dwordx4 v[30:33], v[8:9], off
	v_lshl_add_u64 v[8:9], s[44:45], 0, v[6:7]
	global_load_dwordx4 v[26:29], v[8:9], off
	v_lshl_add_u64 v[8:9], s[84:85], 0, v[6:7]
	global_load_dwordx4 v[46:49], v[8:9], off
	v_lshl_add_u64 v[2:3], s[4:5], 0, v[6:7]
	v_lshl_add_u64 v[6:7], s[86:87], 0, v[6:7]
	global_load_dwordx4 v[6:9], v[6:7], off
	v_readlane_b32 s16, v254, 23
	global_load_dwordx4 v[2:5], v[2:3], off
	v_readlane_b32 s17, v254, 24
	s_waitcnt vmcnt(0)
	v_mov_b32_e32 v59, v70
	v_mov_b32_e32 v23, v71
	v_mov_b32_e32 v53, v72
	v_mov_b32_e32 v25, v73
	v_mov_b32_e32 v57, v74
	v_mov_b32_e32 v15, v75
	v_mov_b32_e32 v55, v76
	v_mov_b32_e32 v17, v77
	v_mov_b32_e32 v58, v78
	v_mov_b32_e32 v22, v79
	v_mov_b32_e32 v52, v80
	v_mov_b32_e32 v24, v81
	v_mov_b32_e32 v56, v82
	v_mov_b32_e32 v14, v83
	v_mov_b32_e32 v54, v84
	v_mov_b32_e32 v16, v85
	v_mov_b32_e32 v63, v34
	v_mov_b32_e32 v62, v42
	v_pk_mul_f32 v[58:59], v[62:63], v[58:59]
	v_mov_b32_e32 v34, v43
	s_waitcnt lgkmcnt(0)
	v_fma_f32 v18, v38, v18, v59
	v_add_f32_e32 v180, v58, v18
	v_mov_b32_e32 v59, v30
	v_mov_b32_e32 v58, v46
	v_pk_mul_f32 v[56:57], v[58:59], v[56:57]
	v_pk_mul_f32 v[22:23], v[34:35], v[22:23]
	v_fma_f32 v10, v26, v10, v57
	v_add_f32_e32 v10, v56, v10
	v_add_f32_e32 v6, v6, v10
	v_mul_f32_e32 v10, 0xbfb8aa3b, v6
	v_exp_f32_e32 v57, v10
	v_mov_b32_e32 v56, v2
	v_pk_add_f32 v[56:57], v[56:57], v[180:181]
	s_nop 0
	v_mul_f32_e32 v2, v56, v6
	v_div_scale_f32 v6, s[14:15], v57, v57, v2
	v_rcp_f32_e32 v10, v6
	s_nop 0
	v_fma_f32 v18, -v6, v10, 1.0
	v_fmac_f32_e32 v10, v18, v10
	v_div_scale_f32 v18, vcc, v2, v57, v2
	v_mul_f32_e32 v26, v18, v10
	v_fma_f32 v30, -v6, v26, v18
	v_fmac_f32_e32 v26, v30, v10
	v_fma_f32 v6, -v6, v26, v18
	v_div_fmas_f32 v6, v6, v10, v26
	v_mov_b32_e32 v30, v47
	v_div_fixup_f32 v2, v6, v57, v2
	v_fma_f32 v6, v39, v19, v23
	v_pk_mul_f32 v[14:15], v[30:31], v[14:15]
	v_add_f32_e32 v180, v22, v6
	v_fma_f32 v6, v27, v11, v15
	v_add_f32_e32 v6, v14, v6
	v_add_f32_e32 v10, v7, v6
	v_mul_f32_e32 v6, 0xbfb8aa3b, v10
	v_exp_f32_e32 v7, v6
	v_mov_b32_e32 v6, v3
	v_pk_add_f32 v[6:7], v[6:7], v[180:181]
	s_nop 0
	v_mul_f32_e32 v3, v6, v10
	v_div_scale_f32 v6, s[14:15], v7, v7, v3
	v_rcp_f32_e32 v10, v6
	s_nop 0
	v_fma_f32 v11, -v6, v10, 1.0
	v_fmac_f32_e32 v10, v11, v10
	v_div_scale_f32 v11, vcc, v3, v7, v3
	v_mul_f32_e32 v14, v11, v10
	v_fma_f32 v15, -v6, v14, v11
	v_fmac_f32_e32 v14, v15, v10
	v_fma_f32 v6, -v6, v14, v11
	v_div_fmas_f32 v6, v6, v10, v14
	v_div_fixup_f32 v3, v6, v7, v3
	v_mov_b32_e32 v6, v44
	v_mov_b32_e32 v7, v36
	v_pk_mul_f32 v[6:7], v[6:7], v[52:53]
	v_mov_b32_e32 v36, v45
	v_fma_f32 v7, v40, v20, v7
	v_add_f32_e32 v180, v6, v7
	v_mov_b32_e32 v6, v48
	v_mov_b32_e32 v7, v32
	v_pk_mul_f32 v[6:7], v[6:7], v[54:55]
	v_mov_b32_e32 v32, v49
	v_fma_f32 v7, v28, v12, v7
	v_add_f32_e32 v6, v6, v7
	v_add_f32_e32 v8, v8, v6
	v_mul_f32_e32 v6, 0xbfb8aa3b, v8
	v_exp_f32_e32 v7, v6
	v_mov_b32_e32 v6, v4
	v_cvt_pk_bf16_f32 v2, v2, v3
	v_pk_add_f32 v[6:7], v[6:7], v[180:181]
	s_nop 0
	v_mul_f32_e32 v4, v6, v8
	v_div_scale_f32 v6, s[14:15], v7, v7, v4
	v_rcp_f32_e32 v8, v6
	s_nop 0
	v_fma_f32 v10, -v6, v8, 1.0
	v_fmac_f32_e32 v8, v10, v8
	v_div_scale_f32 v10, vcc, v4, v7, v4
	v_mul_f32_e32 v11, v10, v8
	v_fma_f32 v12, -v6, v11, v10
	v_fmac_f32_e32 v11, v12, v8
	v_fma_f32 v6, -v6, v11, v10
	v_div_fmas_f32 v6, v6, v8, v11
	v_div_fixup_f32 v8, v6, v7, v4
	v_pk_mul_f32 v[6:7], v[36:37], v[24:25]
	s_nop 0
	v_fma_f32 v4, v41, v21, v7
	v_add_f32_e32 v180, v6, v4
	v_pk_mul_f32 v[6:7], v[32:33], v[16:17]
	s_nop 0
	v_fma_f32 v4, v29, v13, v7
	v_add_f32_e32 v4, v6, v4
	v_add_f32_e32 v9, v9, v4
	v_mul_f32_e32 v4, 0xbfb8aa3b, v9
	v_exp_f32_e32 v7, v4
	v_mov_b32_e32 v6, v5
	v_pk_add_f32 v[4:5], v[6:7], v[180:181]
	s_nop 0
	v_mul_f32_e32 v4, v4, v9
	v_div_scale_f32 v6, s[14:15], v5, v5, v4
	v_rcp_f32_e32 v7, v6
	s_mul_hi_i32 s15, s13, 0x1600
	s_mulk_i32 s13, 0x1600
	s_add_u32 s14, s16, s13
	v_fma_f32 v9, -v6, v7, 1.0
	v_fmac_f32_e32 v7, v9, v7
	v_div_scale_f32 v9, vcc, v4, v5, v4
	v_mul_f32_e32 v10, v9, v7
	v_fma_f32 v11, -v6, v10, v9
	v_fmac_f32_e32 v10, v11, v7
	v_fma_f32 v6, -v6, v10, v9
	v_div_fmas_f32 v6, v6, v7, v10
	v_readlane_b32 s13, v253, 23
	v_div_fixup_f32 v4, v6, v5, v4
	s_addc_u32 s15, s17, s15
	s_add_i32 s11, s11, s24
	v_add_u32_e32 v61, s13, v61
	v_readlane_b32 s13, v253, 24
	v_cvt_pk_bf16_f32 v3, v8, v4
	v_lshl_add_u64 v[4:5], v[50:51], 1, s[14:15]
	s_cmp_ge_i32 s11, s12
	v_add_u32_e32 v60, s13, v60
	flat_store_dwordx2 v[4:5], v[2:3]
	s_cbranch_scc1 .LBB0_715

; __global__ void __launch_bounds__(512, 2) mk_fwd(Args args) {
;     ...
;                 for (int it = gw; it < nitems * 11; it += NGW) {
;                     const int ri = it / 11, chunk = it - ri * 11;
;                     const int g64 = ri >> 1, which = ri & 1; const int row = 64 * g64 + (which ? 63 : 0);
;                     const int tpos = row < ML ? (row & 2047) : ((row - ML) & 255); const int tlen = row < ML ? 2048 : 256;
;                     const float* hc = HALO + (size_t)(g64 * 4 + (which ? 3 : 0)) * FF2;
;                     const float* hp = which ? HALO + (size_t)(g64 * 4 + 2) * FF2 : (tpos > 0 ? HALO + (size_t)((g64 - 1) * 4 + 3) * FF2 : nullptr);
;                     const float* hn = which ? (tpos < tlen - 1 ? HALO + (size_t)((g64 + 1) * 4 + 0) * FF2 : nullptr) : HALO + (size_t)(g64 * 4 + 1) * FF2;
;                     const int c = 256 * chunk + 4 * lane;
;                     const int na = ((c >> 7) << 8) + (c & 127), ng = na + 128;
;                     const f32x4 z4 = (f32x4){0.f, 0.f, 0.f, 0.f};
;                     const f32x4 ac = *(const f32x4*)(hc + na), gc = *(const f32x4*)(hc + ng);
;                     const f32x4 ap = hp ? *(const f32x4*)(hp + na) : z4, gp = hp ? *(const f32x4*)(hp + ng) : z4;
;                     const f32x4 an = hn ? *(const f32x4*)(hn + na) : z4, gn = hn ? *(const f32x4*)(hn + ng) : z4;
.LBB0_707:
	s_and_b64 s[16:17], exec, s[48:49]
	s_cselect_b32 s16, 0, 3
	s_or_b32 s15, s16, s15
	s_mul_hi_i32 s17, s15, 0x5800
	s_mulk_i32 s15, 0x5800
	s_add_u32 s16, s76, s15
	s_mul_i32 s15, s14, 0xffffea00
	v_add_u32_e32 v2, s15, v61
	s_movk_i32 s15, 0xff00
	v_and_or_b32 v2, v2, s15, v0
	s_addc_u32 s17, s77, s17
	v_ashrrev_i32_e32 v3, 31, v2
	v_lshl_add_u64 v[4:5], v[2:3], 2, s[16:17]
	flat_load_dwordx4 v[18:21], v[4:5]
	flat_load_dwordx4 v[10:13], v[4:5] offset:512
	v_mov_b32_e32 v70, 0
	v_mov_b32_e32 v71, 0
	v_mov_b32_e32 v72, 0
	v_mov_b32_e32 v73, 0
	v_mov_b32_e32 v74, 0
	v_mov_b32_e32 v75, 0
	v_mov_b32_e32 v76, 0
	v_mov_b32_e32 v77, 0
	v_mov_b32_e32 v78, 0
	v_mov_b32_e32 v79, 0
	v_mov_b32_e32 v80, 0
	v_mov_b32_e32 v81, 0
	v_mov_b32_e32 v82, 0
	v_mov_b32_e32 v83, 0
	v_mov_b32_e32 v84, 0
	v_mov_b32_e32 v85, 0
	v_lshl_add_u64 v[4:5], v[2:3], 2, s[50:51]
	s_cmp_lg_u64 s[50:51], 0
	s_cbranch_scc0 .Lfix_nohp
	global_load_dwordx4 v[70:73], v[4:5], off
	global_load_dwordx4 v[74:77], v[4:5], off offset:512
.Lfix_nohp:
	v_lshl_add_u64 v[2:3], v[2:3], 2, s[52:53]
	s_cmp_lg_u64 s[52:53], 0
	s_cselect_b64 s[48:49], -1, 0
	s_cbranch_scc0 .Lfix_nohn
	global_load_dwordx4 v[78:81], v[2:3], off
	global_load_dwordx4 v[82:85], v[2:3], off offset:512
.Lfix_nohn:
	s_branch .LBB0_695
.LBB0_715:
	v_readlane_b32 s84, v254, 30
	v_readlane_b32 s86, v254, 32
	v_readlane_b32 s85, v254, 31
	v_readlane_b32 s87, v254, 33
	s_branch .LBB0_673
